# FFN-out K-split: the 5-step slice now goes to the partner workgroups 160..191 (the ones that can still have a conversion item in layers 0/1)
# speedup vs baseline: 1.0041x; 1.0041x over previous
.LBB0_2746:
	s_and_b64 vcc, exec, s[2:3]
	s_cbranch_vccz .LBB0_2881
	v_lshlrev_b32_e32 v0, 4, v56
	v_add_u32_e32 v1, 0x2000, v0
	v_ashrrev_i32_e32 v2, 31, v1
	v_lshrrev_b32_e32 v2, 22, v2
	v_add_u32_e32 v2, v1, v2
	v_ashrrev_i32_e32 v71, 10, v2
	v_mul_i32_i24_e32 v2, 0x400, v71
	v_sub_u32_e32 v1, v1, v2
	v_lshrrev_b32_e32 v2, 4, v1
	v_bitop3_b32 v1, v2, v1, 32 bitop3:0x6c
	v_ashrrev_i32_e32 v2, 31, v1
	v_lshrrev_b32_e32 v2, 26, v2
	v_add_u32_e32 v2, v1, v2
	v_lshlrev_b32_e32 v3, 3, v71
	v_ashrrev_i32_e32 v72, 6, v2
	v_and_b32_e32 v3, -16, v3
	v_add_u32_e32 v3, v72, v3
	v_and_b32_e32 v4, 3, v72
	s_mov_b32 s3, 0xffffe0
	v_lshrrev_b32_e32 v5, 2, v3
	v_lshlrev_b32_e32 v6, 1, v3
	v_and_b32_e32 v2, 0xc0, v2
	v_writelane_b32 v255, s40, 10
	v_and_or_b32 v4, v3, s3, v4
	v_and_b32_e32 v5, 4, v5
	v_and_b32_e32 v6, 24, v6
	v_sub_u32_e32 v1, v1, v2
	v_readlane_b32 s2, v255, 7
	v_or3_b32 v4, v4, v5, v6
	v_lshlrev_b32_e32 v5, 5, v71
	v_ashrrev_i16_sdwa v1, v215, sext(v1) dst_sel:DWORD dst_unused:UNUSED_PAD src0_sel:DWORD src1_sel:BYTE_0
	s_ashr_i32 s95, s2, 6
	v_and_b32_e32 v73, 32, v5
	v_bfe_i32 v74, v1, 0, 16
	s_movk_i32 s2, 0xb00
	v_mul_u32_u24_e32 v4, 0xb00, v4
	v_add_u32_e32 v1, v73, v74
	v_mul_lo_u32 v2, v3, s2
	v_add_lshl_u32 v170, v4, v1, 1
	v_add_lshl_u32 v172, v1, v2, 1
	v_bfe_i32 v1, v56, 27, 1
	v_lshrrev_b32_e32 v1, 22, v1
	v_add_u32_e32 v1, v0, v1
	v_and_b32_e32 v1, 0xfffffc00, v1
	v_sub_u32_e32 v0, v0, v1
	v_lshrrev_b32_e32 v1, 4, v0
	v_ashrrev_i32_e32 v2, 31, v56
	v_bitop3_b32 v0, v1, v0, 32 bitop3:0x6c
	v_lshrrev_b32_e32 v2, 26, v2
	v_ashrrev_i32_e32 v1, 31, v0
	v_add_u32_e32 v2, v56, v2
	v_lshrrev_b32_e32 v1, 26, v1
	v_ashrrev_i32_e32 v76, 6, v2
	v_add_u32_e32 v1, v0, v1
	v_lshlrev_b32_e32 v2, 3, v76
	v_ashrrev_i32_e32 v75, 6, v1
	v_and_b32_e32 v2, -16, v2
	v_add_u32_e32 v2, v75, v2
	v_and_b32_e32 v3, 3, v75
	v_lshrrev_b32_e32 v4, 2, v2
	v_lshlrev_b32_e32 v5, 1, v2
	v_and_b32_e32 v1, 0xc0, v1
	v_and_or_b32 v3, v2, s3, v3
	v_and_b32_e32 v4, 4, v4
	v_and_b32_e32 v5, 24, v5
	v_sub_u32_e32 v0, v0, v1
	s_lshl_b32 s17, s95, 10
	v_or3_b32 v3, v3, v4, v5
	v_lshlrev_b32_e32 v4, 5, v76
	v_ashrrev_i16_sdwa v0, v215, sext(v0) dst_sel:DWORD dst_unused:UNUSED_PAD src0_sel:DWORD src1_sel:BYTE_0
	v_mul_lo_u32 v1, v2, s2
	v_readlane_b32 s2, v254, 19
	v_and_b32_e32 v77, 32, v4
	v_bfe_i32 v78, v0, 0, 16
	s_add_u32 s60, s77, s2
	v_readlane_b32 s2, v254, 17
	v_mul_u32_u24_e32 v3, 0xb00, v3
	v_add_u32_e32 v0, v77, v78
	s_addc_u32 s61, s78, s2
	s_add_i32 s30, s17, 0
	v_add_lshl_u32 v174, v3, v0, 1
	s_add_i32 m0, s30, 0x10000
	v_add_lshl_u32 v176, v0, v1, 1
	global_load_lds_dwordx4 v174, s[60:61]
	s_add_i32 m0, s30, 0x12000
	s_add_u32 s2, s60, 0xb0000
	global_load_lds_dwordx4 v170, s[60:61]
	s_addc_u32 s3, s61, 0
	s_add_i32 m0, s30, 0x14000
	v_writelane_b32 v255, s37, 14
	global_load_lds_dwordx4 v174, s[2:3]
	s_add_i32 m0, s30, 0x16000
	s_nop 0
	global_load_lds_dwordx4 v170, s[2:3]
	v_readlane_b32 s2, v254, 16
	s_add_u32 s58, s75, s2
	v_readlane_b32 s2, v254, 13
	s_addc_u32 s59, s76, s2
	s_add_i32 s31, s30, 0x2000
	s_mov_b32 m0, s30
	s_add_u32 s2, s58, 0xb0000
	global_load_lds_dwordx4 v176, s[58:59]
	s_mov_b32 m0, s31
	s_addc_u32 s3, s59, 0
	s_add_i32 s79, s30, 0x4000
	global_load_lds_dwordx4 v172, s[58:59]
	s_mov_b32 m0, s79
	s_add_i32 s80, s30, 0x6000
	global_load_lds_dwordx4 v176, s[2:3]
	s_mov_b32 m0, s80
	s_abs_i32 s8, s74
	global_load_lds_dwordx4 v172, s[2:3]
	v_cvt_f32_u32_e32 v0, s8
	s_sub_i32 s20, 0, s8
	s_abs_i32 s3, s37
	s_ashr_i32 s2, s37, 31
	v_rcp_iflag_f32_e32 v0, v0
	s_nop 0
	v_mul_f32_e32 v0, 0x4f7ffffe, v0
	v_cvt_u32_f32_e32 v0, v0
	s_nop 0
	v_readfirstlane_b32 s28, v0
	s_mul_i32 s20, s20, s28
	s_mul_hi_u32 s20, s28, s20
	s_add_i32 s28, s28, s20
	s_mul_hi_u32 s20, s3, s28
	s_mul_i32 s20, s20, s8
	s_sub_i32 s3, s3, s20
	s_sub_i32 s20, s3, s8
	s_cmp_ge_u32 s3, s8
	s_cselect_b32 s3, s20, s3
	s_sub_i32 s20, s3, s8
	s_cmp_ge_u32 s3, s8
	s_cselect_b32 s3, s20, s3
	s_xor_b32 s3, s3, s2
	s_sub_i32 s29, s3, s2
	s_mov_b32 s100, 0
	s_mov_b32 s101, 0
	s_cmp_gt_i32 s29, 31
	s_cbranch_scc0 .LBB0_2755
	s_cmpk_lt_i32 s29, 0xa0
	s_cbranch_scc1 .LBB0_2748
	s_sub_i32 s101, s29, 0xa0
	s_lshr_b32 s101, s101, 5
	s_mul_i32 s100, s101, 0xc0
	s_cmp_eq_u32 s101, 0
	s_cselect_b32 s100, 0x220, s100
	s_mov_b32 s101, 0
	s_and_b32 s29, s29, 31
	s_branch .LBB0_2755

.LBB0_2908:
	s_and_b64 vcc, exec, s[2:3]
	s_cbranch_vccz .LBB0_2985
	v_lshlrev_b32_e32 v0, 4, v26
	s_waitcnt lgkmcnt(0)
	v_add_u32_e32 v1, 0x2000, v0
	v_ashrrev_i32_e32 v2, 31, v1
	v_lshrrev_b32_e32 v2, 22, v2
	v_add_u32_e32 v2, v1, v2
	v_ashrrev_i32_e32 v28, 10, v2
	v_mul_i32_i24_e32 v2, 0x400, v28
	v_sub_u32_e32 v1, v1, v2
	v_lshrrev_b32_e32 v2, 4, v1
	v_bitop3_b32 v1, v2, v1, 32 bitop3:0x6c
	v_ashrrev_i32_e32 v2, 31, v1
	v_lshrrev_b32_e32 v2, 26, v2
	v_add_u32_e32 v2, v1, v2
	v_lshlrev_b32_e32 v3, 3, v28
	v_ashrrev_i32_e32 v29, 6, v2
	v_and_b32_e32 v3, -16, v3
	v_add_u32_e32 v3, v29, v3
	v_and_b32_e32 v4, 3, v29
	s_mov_b32 s1, 0xffffe0
	v_lshrrev_b32_e32 v5, 2, v3
	v_lshlrev_b32_e32 v6, 1, v3
	v_and_b32_e32 v2, 0xc0, v2
	v_and_or_b32 v4, v3, s1, v4
	v_and_b32_e32 v5, 4, v5
	v_and_b32_e32 v6, 24, v6
	v_sub_u32_e32 v1, v1, v2
	v_or3_b32 v4, v4, v5, v6
	v_lshlrev_b32_e32 v5, 5, v28
	v_ashrrev_i16_sdwa v1, v215, sext(v1) dst_sel:DWORD dst_unused:UNUSED_PAD src0_sel:DWORD src1_sel:BYTE_0
	v_and_b32_e32 v30, 32, v5
	v_bfe_i32 v31, v1, 0, 16
	s_movk_i32 s0, 0xb00
	v_mul_u32_u24_e32 v4, 0xb00, v4
	v_add_u32_e32 v1, v30, v31
	v_mul_lo_u32 v2, v3, s0
	v_add_lshl_u32 v130, v4, v1, 1
	v_add_lshl_u32 v132, v1, v2, 1
	v_bfe_i32 v1, v26, 27, 1
	v_lshrrev_b32_e32 v1, 22, v1
	v_add_u32_e32 v1, v0, v1
	v_and_b32_e32 v1, 0xfffffc00, v1
	v_sub_u32_e32 v0, v0, v1
	v_lshrrev_b32_e32 v1, 4, v0
	v_ashrrev_i32_e32 v2, 31, v26
	v_bitop3_b32 v0, v1, v0, 32 bitop3:0x6c
	v_lshrrev_b32_e32 v2, 26, v2
	v_ashrrev_i32_e32 v1, 31, v0
	v_add_u32_e32 v2, v26, v2
	v_lshrrev_b32_e32 v1, 26, v1
	v_ashrrev_i32_e32 v35, 6, v2
	v_add_u32_e32 v1, v0, v1
	v_lshlrev_b32_e32 v2, 3, v35
	v_ashrrev_i32_e32 v34, 6, v1
	v_and_b32_e32 v2, -16, v2
	v_add_u32_e32 v2, v34, v2
	v_and_b32_e32 v3, 3, v34
	v_lshrrev_b32_e32 v4, 2, v2
	v_lshlrev_b32_e32 v5, 1, v2
	v_and_b32_e32 v1, 0xc0, v1
	s_ashr_i32 s19, s8, 6
	v_and_or_b32 v3, v2, s1, v3
	v_and_b32_e32 v4, 4, v4
	v_and_b32_e32 v5, 24, v5
	v_sub_u32_e32 v0, v0, v1
	s_lshl_b32 s11, s19, 10
	v_or3_b32 v3, v3, v4, v5
	v_lshlrev_b32_e32 v4, 5, v35
	v_ashrrev_i16_sdwa v0, v215, sext(v0) dst_sel:DWORD dst_unused:UNUSED_PAD src0_sel:DWORD src1_sel:BYTE_0
	v_mul_lo_u32 v1, v2, s0
	v_readlane_b32 s0, v254, 19
	v_and_b32_e32 v36, 32, v4
	v_bfe_i32 v37, v0, 0, 16
	s_add_u32 s52, s77, s0
	v_readlane_b32 s0, v254, 17
	v_mul_u32_u24_e32 v3, 0xb00, v3
	v_add_u32_e32 v0, v36, v37
	s_addc_u32 s53, s78, s0
	s_add_i32 s12, s11, 0
	v_add_lshl_u32 v32, v3, v0, 1
	s_add_i32 m0, s12, 0x10000
	v_readlane_b32 s0, v254, 16
	global_load_lds_dwordx4 v32, s[52:53]
	s_add_i32 m0, s12, 0x12000
	s_add_u32 s2, s52, 0xb0000
	global_load_lds_dwordx4 v130, s[52:53]
	s_addc_u32 s3, s53, 0
	s_add_i32 m0, s12, 0x14000
	v_add_lshl_u32 v134, v0, v1, 1
	global_load_lds_dwordx4 v32, s[2:3]
	s_add_i32 m0, s12, 0x16000
	s_add_u32 s40, s75, s0
	v_readlane_b32 s0, v254, 13
	s_addc_u32 s41, s76, s0
	s_add_i32 s14, s12, 0x2000
	global_load_lds_dwordx4 v130, s[2:3]
	s_mov_b32 m0, s12
	s_add_u32 s2, s40, 0xb0000
	global_load_lds_dwordx4 v134, s[40:41]
	s_mov_b32 m0, s14
	s_addc_u32 s3, s41, 0
	s_add_i32 s15, s12, 0x4000
	global_load_lds_dwordx4 v132, s[40:41]
	s_mov_b32 m0, s15
	s_add_i32 s17, s12, 0x6000
	global_load_lds_dwordx4 v134, s[2:3]
	s_mov_b32 m0, s17
	v_and_b32_e32 v145, 64, v216
	global_load_lds_dwordx4 v132, s[2:3]
	s_ashr_i32 s2, s37, 31
	s_lshr_b32 s2, s2, 24
	s_add_i32 s2, s37, s2
	s_and_b32 s2, s2, 0xffffff00
	s_sub_i32 s13, s37, s2
	s_mov_b32 s100, 0
	s_mov_b32 s101, 0
	s_cmp_gt_i32 s13, 31
	v_xor_b32_e32 v144, 16, v216
	s_movk_i32 s0, 0x1ff
	s_cbranch_scc0 .Lsp2_go
	s_cmpk_lt_i32 s13, 0xa0
	s_cbranch_scc1 .LBB0_2933
	s_sub_i32 s101, s13, 0xa0
	s_lshr_b32 s101, s101, 5
	s_mul_i32 s100, s101, 0xc0
	s_cmp_eq_u32 s101, 0
	s_cselect_b32 s100, 0x220, s100
	s_mov_b32 s101, 0
	s_and_b32 s13, s13, 31
